# attention loops: a single compare of the tile max against the per-row threshold decides the common case; reference/max bookkeeping moved to the rare path
# speedup vs baseline: 1.0021x; 1.0021x over previous
; template <int MODE>
; __device__ __forceinline__ void attn_unit(LAS char* lds, const AttnPtrs& A, int b, int qb) {
;     ...
;     const int tid = opaque_tid(), lane = tid & 63, r32 = lane & 31, hi = lane >> 5, wid = __builtin_amdgcn_readfirstlane(tid >> 6);
;     const int strm = (MODE == 2) ? (wid & 1) : 0;
;     const size_t rowbase = (size_t)b * SEQ; const int q0 = (MODE == 2) ? qb * 128 + (wid >> 1) * 32 : qb * 256 + wid * 32; const int cw = q0 >> 6, NT = (MODE == 2) ? 2 * qb + 2 : 4 * qb + 4;
;     const size_t qrow = rowbase + q0 + r32;
;     const bf16_t* ksrc[2]; const bf16_t* vsrc[2];
; #pragma unroll
;     for (int i = 0; i < 2; ++i) { const unsigned row = 4u * (2 * wid + i) + (lane >> 4), ch = (lane & 15) ^ (((row & 3) << 2) | ((row >> 2) & 3));
;         ksrc[i] = A.K + (rowbase + row) * A.ldk + ch * 8; vsrc[i] = A.V + (rowbase + row) * A.ldv + ch * 8; }
;     const bf16_t* k64src = nullptr;
;     if constexpr (MODE == 0) { const unsigned row = 8u * wid + (lane >> 3), ch = (lane & 7) ^ ((row >> 1) & 7); k64src = A.K64 + (rowbase + row) * 64 + ch * 8; }
;     const unsigned fK = ((r32 & 3) << 2) | ((r32 >> 2) & 3);
;     const unsigned g64 = (r32 >> 1) & 7;
;     const int q4 = (lane & 15) >> 2, p4 = lane & 3, blk = (lane >> 4) & 1;
;     unsigned vrow[2], vlow[2];
; #pragma unroll
;     for (int t = 0; t < 2; ++t) { vrow[t] = 4 * hi + 8 * t + q4; vlow[t] = (unsigned)((2 * blk + (p4 >> 1)) ^ ((hi + 2 * t) & 3)); }
;     ...
;     STAGE(0, 0); STAGE(1, 1);
;     bf16x8 qf[NQ];
; #pragma unroll
;     for (int s = 0; s < NQ; ++s) qf[s] = *(const bf16x8*)(A.Q + qrow * A.ldq + 64 * strm + 16 * s + 8 * hi);
;     ...
;                 const int qb = 31 - it / 20, bh = it % 20, b = bh / 5, h = bh % 5;
;                 att::AttnPtrs A{QKC + 2 * h * 64, 1280, QKC + 640 + 2 * h * 64, 1280, nullptr, VBC + 640 + h * 128, 1280, GATE + 1408 + h * 128, GATE + 1408 + h * 128, nullptr, lam, 1.0f - lam_init, ap->subln_g + L * 128};
.LBB0_623:
	s_mul_hi_i32 s3, s2, 0x99999999
	s_lshr_b32 s4, s3, 31
	s_ashr_i32 s3, s3, 3
	s_add_i32 s3, s3, s4
	s_mul_hi_i32 s4, s2, 0x66666667
	s_lshr_b32 s5, s4, 31
	s_lshr_b32 s4, s4, 3
	s_add_i32 s4, s4, s5
	s_mul_i32 s4, s4, 20
	s_sub_i32 s4, s2, s4
	s_bfe_i32 s2, s4, 0x80000
	s_mulk_i32 s2, 0x67
	s_sext_i32_i16 s5, s2
	s_ashr_i32 s5, s5, 9
	s_bfe_u32 s2, s2, 0x1000f
	s_add_i32 s2, s5, s2
	s_mul_i32 s5, s2, 5
	s_sub_i32 s4, s4, s5
	s_sext_i32_i8 s4, s4
	s_lshl_b32 s4, s4, 7
	s_ashr_i32 s5, s4, 31
	s_add_i32 s24, s3, 31
	s_lshl_b64 s[4:5], s[4:5], 1
	s_add_u32 s6, s10, s4
	s_addc_u32 s7, s11, s5
	s_add_u32 s28, s12, s4
	s_addc_u32 s29, s13, s5
	s_add_u32 s34, s18, s4
	s_getreg_b32 s8, hwreg(HW_REG_HW_ID, 0, 6)
	s_addc_u32 s35, s19, s5
	s_lshl_b32 s8, s8, 2
	s_and_b32 s8, s8, 0xfc
	s_add_i32 s8, s8, 0x20040
	v_mov_b32_e32 v0, s8
	ds_read_b32 v0, v0
	s_lshl_b32 s25, s24, 7
	v_mov_b64_e32 v[8:9], s[28:29]
	v_mov_b64_e32 v[12:13], s[34:35]
	s_lshl_b32 s24, s24, 1
	s_waitcnt lgkmcnt(0)
	v_readfirstlane_b32 s8, v0
	v_mov_b32_e32 v0, v1
	v_mov_b32_e32 v3, v1
	v_mbcnt_lo_u32_b32 v0, -1, v0
	v_mbcnt_hi_u32_b32 v6, -1, v0
	v_lshl_or_b32 v0, s8, 6, v6
	s_bfe_i64 s[8:9], s[2:3], 0x100000
	v_readfirstlane_b32 s23, v0
	s_ashr_i32 s26, s23, 6
	s_ashr_i32 s23, s23, 7
	s_lshl_b32 s27, s23, 5
	s_add_i32 s27, s27, s25
	s_lshl_b32 s25, s26, 3
	v_bfe_u32 v16, v6, 4, 2
	s_lshl_b64 s[8:9], s[8:9], 12
	v_or_b32_e32 v0, s25, v16
	v_lshl_add_u64 v[4:5], s[8:9], 0, v[0:1]
	s_lshl_b32 s44, s26, 1
	v_mad_u64_u32 v[10:11], s[28:29], v4, s84, v[8:9]
	v_mad_u64_u32 v[14:15], s[28:29], v4, s84, v[12:13]
	s_or_b32 s25, s25, 4
	v_and_b32_e32 v17, 15, v6
	v_lshlrev_b32_e32 v18, 2, v16
	s_and_b32 s44, s44, 2
	v_mad_i32_i24 v11, v5, s84, v11
	v_mad_i32_i24 v15, v5, s84, v15
	v_or_b32_e32 v4, s25, v16
	s_bfe_u32 s25, s25, 0x20002
	v_mov_b32_e32 v5, v1
	s_ashr_i32 s33, s27, 31
	v_bitop3_b32 v2, s44, v17, v18 bitop3:0x36
	v_bitop3_b32 v18, s25, v17, v18 bitop3:0x36
	v_lshl_add_u64 v[16:17], s[8:9], 0, v[4:5]
	s_ashr_i32 s25, s27, 6
	v_mad_u64_u32 v[8:9], s[28:29], v16, s84, v[8:9]
	v_mad_u64_u32 v[12:13], s[28:29], v16, s84, v[12:13]
	s_add_u32 s27, s8, s27
	s_addc_u32 s28, s9, s33
	s_lshl_b32 s9, s26, 11
	v_lshlrev_b32_e32 v2, 4, v2
	s_add_i32 s9, s9, 0
	v_lshl_add_u64 v[10:11], v[10:11], 0, v[2:3]
	v_mad_i32_i24 v9, v17, s84, v9
	v_lshlrev_b32_e32 v4, 4, v18
	s_mov_b32 m0, s9
	v_lshl_add_u64 v[8:9], v[8:9], 0, v[4:5]
	global_load_lds_dwordx4 v[10:11], off
	s_add_i32 m0, s9, 0x400
	v_lshl_add_u64 v[14:15], v[14:15], 0, v[2:3]
	v_mad_i32_i24 v13, v17, s84, v13
	global_load_lds_dwordx4 v[8:9], off
	s_add_i32 m0, s9, 0x4000
	v_lshl_add_u64 v[12:13], v[12:13], 0, v[4:5]
	global_load_lds_dwordx4 v[14:15], off
	s_add_i32 m0, s9, 0x4400
	v_lshl_add_u64 v[10:11], v[10:11], 0, s[60:61]
	global_load_lds_dwordx4 v[12:13], off
	s_add_i32 m0, s9, 0xa000
	v_lshl_add_u64 v[8:9], v[8:9], 0, s[60:61]
	global_load_lds_dwordx4 v[10:11], off
	s_add_i32 m0, s9, 0xa400
	v_and_b32_e32 v7, 31, v6
	global_load_lds_dwordx4 v[8:9], off
	v_lshl_add_u64 v[8:9], v[14:15], 0, s[60:61]
	s_add_i32 m0, s9, 0xe000
	v_or_b32_e32 v114, s27, v7
	global_load_lds_dwordx4 v[8:9], off
	v_lshl_add_u64 v[8:9], v[12:13], 0, s[60:61]
	s_add_i32 m0, s9, 0xe400
	s_and_b32 s8, s26, 1
	global_load_lds_dwordx4 v[8:9], off
	v_mov_b64_e32 v[8:9], s[6:7]
	v_mad_u64_u32 v[8:9], s[6:7], v114, s84, v[8:9]
	v_mov_b32_e32 v10, 0xa00
	v_bfe_u32 v16, v6, 5, 1
	v_mad_i32_i24 v9, s28, v10, v9
	s_lshl_b32 s68, s8, 7
	v_lshl_add_u64 v[8:9], v[8:9], 0, s[68:69]
	v_lshlrev_b32_e32 v10, 4, v16
	v_mov_b32_e32 v11, v1
	v_lshl_add_u64 v[8:9], v[8:9], 0, v[10:11]
	global_load_dwordx4 v[98:101], v[8:9], off
	global_load_dwordx4 v[102:105], v[8:9], off offset:32
	global_load_dwordx4 v[106:109], v[8:9], off offset:64
	global_load_dwordx4 v[110:113], v[8:9], off offset:96
	v_lshlrev_b32_e32 v17, 2, v6
	v_bfe_u32 v18, v6, 2, 2
	v_and_or_b32 v8, v17, 12, v18
	s_lshl_b32 s6, s8, 3
	v_lshlrev_b32_e32 v9, 3, v6
	v_mov_b32_e32 v10, 0x4000
	v_lshrrev_b32_e32 v19, 3, v6
	v_lshlrev_b32_e32 v124, 8, v7
	v_or_b32_e32 v7, s6, v16
	v_and_or_b32 v125, v9, 8, v10
	v_bitop3_b32 v9, s6, v8, v16 bitop3:0x36
	v_and_b32_e32 v19, 2, v19
	v_bfe_u32 v20, v6, 1, 1
	v_lshlrev_b32_e32 v126, 4, v9
	v_bitop3_b32 v9, v7, v8, 2 bitop3:0x36
	v_or_b32_e32 v21, v19, v20
	v_lshlrev_b32_e32 v127, 4, v9
	v_bitop3_b32 v9, v7, v8, 4 bitop3:0x36
	v_bitop3_b32 v7, v7, v8, 6 bitop3:0x36
	v_bitop3_b32 v19, v19, v16, v20 bitop3:0x36
	v_bitop3_b32 v23, v16, v21, 2 bitop3:0x36
	v_lshlrev_b32_e32 v129, 4, v7
	v_and_b32_e32 v7, 12, v6
	v_or_b32_e32 v8, v19, v7
	v_or_b32_e32 v7, v23, v7
	v_or_b32_e32 v20, 2, v16
	v_lshlrev_b32_e32 v133, 4, v7
	v_bitop3_b32 v7, v6, 4, 12 bitop3:0x6c
	v_lshlrev_b32_e32 v131, 4, v8
	v_bitop3_b32 v8, v21, v7, v16 bitop3:0xde
	v_bitop3_b32 v7, v20, v7, v21 bitop3:0xde
	v_lshlrev_b32_e32 v141, 4, v7
	v_bitop3_b32 v7, v6, 8, 12 bitop3:0x6c
	v_and_b32_e32 v123, 63, v6
	v_lshlrev_b32_e32 v140, 4, v8
	v_bitop3_b32 v8, v21, v7, v16 bitop3:0xde
	v_bitop3_b32 v7, v20, v7, v21 bitop3:0xde
	v_bitop3_b32 v6, v6, 12, v6 bitop3:0xc
	v_lshlrev_b32_e32 v143, 4, v7
	v_bitop3_b32 v7, v21, v6, v16 bitop3:0xde
	v_bitop3_b32 v6, v20, v6, v21 bitop3:0xde
	v_lshlrev_b32_e32 v145, 4, v6
	v_or_b32_e32 v6, 4, v0
	v_lshlrev_b32_e32 v144, 4, v7
	v_mad_u64_u32 v[6:7], s[6:7], v6, s84, 0
	s_sext_i32_i16 s2, s2
	v_mad_i64_i32 v[6:7], s[6:7], s2, v214, v[6:7]
	v_lshl_add_u64 v[4:5], v[6:7], 0, v[4:5]
	v_lshl_add_u64 v[116:117], s[14:15], 0, v[4:5]
	v_mad_u64_u32 v[4:5], s[6:7], v0, s84, 0
	v_lshlrev_b32_e32 v122, 2, v16
	v_mad_i64_i32 v[4:5], s[6:7], s2, v214, v[4:5]
	v_or_b32_e32 v22, v122, v18
	v_lshl_add_u64 v[2:3], v[4:5], 0, v[2:3]
	v_mov_b32_e32 v14, v1
	v_mov_b32_e32 v15, v1
	s_waitcnt vmcnt(0)
	s_waitcnt vmcnt(0) lgkmcnt(0)
	s_barrier
; template <int MODE>
; __device__ __forceinline__ void attn_unit(LAS char* lds, const AttnPtrs& A, int b, int qb) {
;     ...
;     f32x16 o1[4];
; #pragma unroll
;     for (int c = 0; c < 4; ++c) o1[c] = f32x16{};
;     float m1 = -1e30f, l1 = 0.f;
;     unsigned long long mw_next = 0ull;
;     if constexpr (MODE == 1) { mw_next = A.MASK[qrow * 64]; asm volatile("" : "+v"(mw_next)); }
;     bf16x8 pk[4]; float a1 = 1.f;
;     ...
;     int st_cur = 0, st_nn = 2;
	v_lshlrev_b32_e32 v128, 4, v9
	v_lshlrev_b32_e32 v130, 8, v22
	v_lshlrev_b32_e32 v142, 4, v8
	v_lshl_add_u64 v[118:119], s[14:15], 0, v[2:3]
	v_mov_b32_e32 v0, v1
	v_mov_b32_e32 v2, v1
	v_mov_b32_e32 v3, v1
	v_mov_b32_e32 v4, v1
	v_mov_b32_e32 v5, v1
	v_mov_b32_e32 v6, v1
	v_mov_b32_e32 v7, v1
	v_mov_b32_e32 v8, v1
	v_mov_b32_e32 v9, v1
	v_mov_b32_e32 v10, v1
	v_mov_b32_e32 v12, v1
	v_mov_b32_e32 v13, v1
	v_mov_b64_e32 v[64:65], v[14:15]
	v_mov_b64_e32 v[48:49], v[14:15]
	v_mov_b64_e32 v[32:33], v[14:15]
	s_lshl_b32 s6, s3, 1
	v_mov_b64_e32 v[62:63], v[12:13]
	v_mov_b64_e32 v[60:61], v[10:11]
	v_mov_b64_e32 v[58:59], v[8:9]
	v_mov_b64_e32 v[56:57], v[6:7]
	v_mov_b64_e32 v[54:55], v[4:5]
	v_mov_b64_e32 v[52:53], v[2:3]
	v_mov_b64_e32 v[50:51], v[0:1]
	v_mov_b64_e32 v[46:47], v[12:13]
	v_mov_b64_e32 v[44:45], v[10:11]
	v_mov_b64_e32 v[42:43], v[8:9]
	v_mov_b64_e32 v[40:41], v[6:7]
	v_mov_b64_e32 v[38:39], v[4:5]
	v_mov_b64_e32 v[36:37], v[2:3]
	v_mov_b64_e32 v[34:35], v[0:1]
	v_mov_b64_e32 v[30:31], v[12:13]
	v_mov_b64_e32 v[28:29], v[10:11]
	v_mov_b64_e32 v[26:27], v[8:9]
	v_mov_b64_e32 v[24:25], v[6:7]
	v_mov_b64_e32 v[22:23], v[4:5]
	v_mov_b64_e32 v[20:21], v[2:3]
	v_mov_b64_e32 v[18:19], v[0:1]
	v_mov_b64_e32 v[16:17], v[14:15]
	s_mov_b32 s16, 2
	s_mov_b32 s17, 0
	v_mov_b32_e32 v115, s28
	v_or_b32_e32 v132, 0x800, v130
	v_or_b32_e32 v134, 0x1000, v130
	v_or_b32_e32 v135, 0x1800, v130
	v_or_b32_e32 v136, 0x2000, v130
	v_or_b32_e32 v137, 0x2800, v130
	v_or_b32_e32 v138, 0x3000, v130
	v_or_b32_e32 v139, 0x3800, v130
	s_add_i32 s6, s6, 64
	v_mov_b32_e32 v148, 0xf149f2ca
	v_mov_b32_e32 v253, s97
	v_mov_b32_e32 v252, 0
	v_mov_b64_e32 v[236:237], 0
	v_mov_b64_e32 v[238:239], 0
	v_mov_b64_e32 v[240:241], 0
	v_mov_b64_e32 v[242:243], 0
	v_mov_b64_e32 v[244:245], 0
	v_mov_b64_e32 v[246:247], 0
	v_mov_b64_e32 v[248:249], 0
	v_mov_b64_e32 v[250:251], 0
	v_mov_b32_e32 v147, 0
	v_mov_b64_e32 v[14:15], v[12:13]
	v_mov_b64_e32 v[12:13], v[10:11]
	v_mov_b64_e32 v[10:11], v[8:9]
	v_mov_b64_e32 v[8:9], v[6:7]
	v_mov_b64_e32 v[6:7], v[4:5]
	v_mov_b64_e32 v[4:5], v[2:3]
	v_mov_b64_e32 v[2:3], v[0:1]
	s_mov_b32 s7, 0
	s_cmp_ge_u32 s7, s24
	s_cselect_b64 s[2:3], -1, 0
	s_and_b64 vcc, exec, s[2:3]
	s_cbranch_vccnz .LBB0_626
	s_branch .LBB0_625

; __device__ __forceinline__ float max_x32(float v) { const unsigned u = __float_as_uint(v); auto r = __builtin_amdgcn_permlane32_swap(u, u, false, false); return fmaxf(__uint_as_float(r[0]), __uint_as_float(r[1])); }
; template <bool MASKED>
; __device__ __forceinline__ void softmax_tile(f32x16& s0, f32x16& s1, float& m, float& l, float& alpha, unsigned mlo, unsigned mhi, bf16x8 (&pk)[4]) {
;     ...
;     float mx = fmaxf(s0[0], s1[0]);
; #pragma unroll
;     for (int r = 1; r < 16; ++r) mx = fmaxf(mx, fmaxf(s0[r], s1[r]));
;     mx = max_x32(mx);
;     const float mn = fmaxf(m, mx);
;     alpha = __builtin_amdgcn_exp2f(m - mn); m = mn;
.LBB0_626:
	s_cmp_gt_i32 s7, s25
	s_cbranch_scc1 .LBB0_630
	s_mul_i32 s26, s17, 0xa000
	s_add_i32 s26, s26, 0
	v_add_u32_e32 v0, s26, v124
	v_add_u32_e32 v70, v0, v126
	v_add_u32_e32 v74, v0, v127
	ds_read_b128 v[66:69], v70
	ds_read_b128 v[70:73], v70 offset:8192
	ds_read_b128 v[150:153], v74
	ds_read_b128 v[154:157], v74 offset:8192
	v_add_u32_e32 v74, v0, v128
	v_add_u32_e32 v0, v0, v129
	ds_read_b128 v[158:161], v74
	ds_read_b128 v[162:165], v74 offset:8192
	ds_read_b128 v[166:169], v0
	ds_read_b128 v[170:173], v0 offset:8192
	s_waitcnt lgkmcnt(0)
	v_mfma_f32_32x32x16_bf16 v[82:97], v[66:69], v[98:101], v[236:251]
	v_mfma_f32_32x32x16_bf16 v[66:81], v[70:73], v[98:101], v[236:251]
	v_mfma_f32_32x32x16_bf16 v[82:97], v[150:153], v[102:105], v[82:97]
	v_mfma_f32_32x32x16_bf16 v[66:81], v[154:157], v[102:105], v[66:81]
	v_mfma_f32_32x32x16_bf16 v[82:97], v[158:161], v[106:109], v[82:97]
	v_mfma_f32_32x32x16_bf16 v[66:81], v[162:165], v[106:109], v[66:81]
	v_mfma_f32_32x32x16_bf16 v[82:97], v[166:169], v[110:113], v[82:97]
	v_mfma_f32_32x32x16_bf16 v[66:81], v[170:173], v[110:113], v[66:81]
	s_nop 11
	v_max3_f32 v150, v82, v83, v84
	v_max3_f32 v151, v85, v86, v87
	v_max3_f32 v152, v88, v89, v90
	v_max3_f32 v153, v91, v92, v93
	v_max3_f32 v154, v94, v95, v96
	v_max3_f32 v155, v97, v66, v67
	v_max3_f32 v156, v68, v69, v70
	v_max3_f32 v157, v71, v72, v73
	v_max3_f32 v158, v74, v75, v76
	v_max3_f32 v159, v77, v78, v79
	v_max3_f32 v150, v150, v151, v152
	v_max3_f32 v153, v153, v154, v155
	v_max3_f32 v156, v156, v157, v158
	v_max3_f32 v159, v159, v80, v81
	v_max3_f32 v150, v150, v153, v156
	v_max_f32_e32 v150, v150, v159
	v_mov_b32_e32 v151, v150
	s_nop 1
	v_permlane32_swap_b32_e32 v150, v151
	v_max_f32_e32 v150, v150, v151
	v_mov_b32_e32 v0, 1.0
	v_mov_b32_e32 v146, v148
	v_cmp_lt_f32_e32 vcc, v253, v150
	s_cbranch_vccz .Lm2_cfast
	v_add_f32_e32 v151, v150, v252
	v_cndmask_b32_e32 v146, v148, v151, vcc
	v_sub_f32_e32 v151, v146, v252
	v_cndmask_b32_e32 v151, 0, v151, vcc
	v_mov_b32_e32 v150, 0x41000000
	v_cndmask_b32_e32 v253, v253, v150, vcc
	v_cndmask_b32_e32 v252, v252, v146, vcc
	v_sub_f32_e32 v0, v148, v146
	v_exp_f32_e32 v0, v0
	v_sub_f32_e32 v82, v82, v151
	v_sub_f32_e32 v83, v83, v151
	v_sub_f32_e32 v84, v84, v151
	v_sub_f32_e32 v85, v85, v151
	v_sub_f32_e32 v86, v86, v151
	v_sub_f32_e32 v87, v87, v151
	v_sub_f32_e32 v88, v88, v151
	v_sub_f32_e32 v89, v89, v151
	v_sub_f32_e32 v90, v90, v151
	v_sub_f32_e32 v91, v91, v151
	v_sub_f32_e32 v92, v92, v151
	v_sub_f32_e32 v93, v93, v151
	v_sub_f32_e32 v94, v94, v151
	v_sub_f32_e32 v95, v95, v151
	v_sub_f32_e32 v96, v96, v151
	v_sub_f32_e32 v97, v97, v151
	v_sub_f32_e32 v66, v66, v151
	v_sub_f32_e32 v67, v67, v151
	v_sub_f32_e32 v68, v68, v151
	v_sub_f32_e32 v69, v69, v151
	v_sub_f32_e32 v70, v70, v151
	v_sub_f32_e32 v71, v71, v151
	v_sub_f32_e32 v72, v72, v151
	v_sub_f32_e32 v73, v73, v151
	v_sub_f32_e32 v74, v74, v151
	v_sub_f32_e32 v75, v75, v151
	v_sub_f32_e32 v76, v76, v151
	v_sub_f32_e32 v77, v77, v151
	v_sub_f32_e32 v78, v78, v151
	v_sub_f32_e32 v79, v79, v151
	v_sub_f32_e32 v80, v80, v151
	v_sub_f32_e32 v81, v81, v151
	v_sub_f32_e32 v236, 0, v252
	v_sub_f32_e32 v237, 0, v252
	v_sub_f32_e32 v238, 0, v252
	v_sub_f32_e32 v239, 0, v252
	v_sub_f32_e32 v240, 0, v252
	v_sub_f32_e32 v241, 0, v252
	v_sub_f32_e32 v242, 0, v252
	v_sub_f32_e32 v243, 0, v252
	v_sub_f32_e32 v244, 0, v252
	v_sub_f32_e32 v245, 0, v252
	v_sub_f32_e32 v246, 0, v252
	v_sub_f32_e32 v247, 0, v252
	v_sub_f32_e32 v248, 0, v252
	v_sub_f32_e32 v249, 0, v252
	v_sub_f32_e32 v250, 0, v252
	v_sub_f32_e32 v251, 0, v252

; template <int MODE>
; __device__ __forceinline__ void attn_unit(LAS char* lds, const AttnPtrs& A, int b, int qb) {
;     ...
;     const int tid = opaque_tid(), lane = tid & 63, r32 = lane & 31, hi = lane >> 5, wid = __builtin_amdgcn_readfirstlane(tid >> 6);
;     const int strm = (MODE == 2) ? (wid & 1) : 0;
;     const size_t rowbase = (size_t)b * SEQ; const int q0 = (MODE == 2) ? qb * 128 + (wid >> 1) * 32 : qb * 256 + wid * 32; const int cw = q0 >> 6, NT = (MODE == 2) ? 2 * qb + 2 : 4 * qb + 4;
;     const size_t qrow = rowbase + q0 + r32;
;     const bf16_t* ksrc[2]; const bf16_t* vsrc[2];
; #pragma unroll
;     for (int i = 0; i < 2; ++i) { const unsigned row = 4u * (2 * wid + i) + (lane >> 4), ch = (lane & 15) ^ (((row & 3) << 2) | ((row >> 2) & 3));
;         ksrc[i] = A.K + (rowbase + row) * A.ldk + ch * 8; vsrc[i] = A.V + (rowbase + row) * A.ldv + ch * 8; }
;     const bf16_t* k64src = nullptr;
;     if constexpr (MODE == 0) { const unsigned row = 8u * wid + (lane >> 3), ch = (lane & 7) ^ ((row >> 1) & 7); k64src = A.K64 + (rowbase + row) * 64 + ch * 8; }
;     const unsigned fK = ((r32 & 3) << 2) | ((r32 >> 2) & 3);
;     const unsigned g64 = (r32 >> 1) & 7;
;     const int q4 = (lane & 15) >> 2, p4 = lane & 3, blk = (lane >> 4) & 1;
;     unsigned vrow[2], vlow[2];
; #pragma unroll
;     for (int t = 0; t < 2; ++t) { vrow[t] = 4 * hi + 8 * t + q4; vlow[t] = (unsigned)((2 * blk + (p4 >> 1)) ^ ((hi + 2 * t) & 3)); }
;     ...
;     STAGE(0, 0); STAGE(1, 1);
;     bf16x8 qf[NQ];
; #pragma unroll
;     for (int s = 0; s < NQ; ++s) qf[s] = *(const bf16x8*)(A.Q + qrow * A.ldq + 64 * strm + 16 * s + 8 * hi);
;     if constexpr (MODE == 0) {
; #pragma unroll
;     ...
;             for (int it = bx;;) {
;                 if (it >= 704) break;
;                 const int qb = 15 - it / 44, w = it % 44;
;                 if (w < 24) { const int b = w / 6, h = w % 6;
;                     att::AttnPtrs A{QMLA + h * 192, NUQ, KMLA + h * 128, 768, KROPE, VMLA + h * 128, 768, GATE + h * 128, GATE + h * 128, nullptr, 0.f, 0.f, (const float*)TAB};
;     ...
;                     att::attn_unit<0>((LAS char*)lds, A, b, qb);
;     ...
;                 } else { const int w2 = w - 24, b = w2 / 5, h = w2 % 5;
;                     att::AttnPtrs A{QKB + h * 128, 1280, QKB + 640 + h * 128, 1280, nullptr, VBC + h * 128, 1280, GATE + 768 + h * 128, GATE + 768 + h * 128, MASK, 0.f, 0.f, nullptr};
.LBB0_1168:
	s_mul_hi_i32 s1, s0, 0xd1745d17
	s_lshr_b32 s12, s1, 31
	s_ashr_i32 s1, s1, 3
	s_add_i32 s49, s1, s12
	s_mul_hi_i32 s1, s0, 0x2e8ba2e9
	s_lshr_b32 s12, s1, 31
	s_ashr_i32 s1, s1, 3
	s_add_i32 s1, s1, s12
	s_mul_i32 s1, s1, 44
	s_add_i32 s49, s49, 15
	s_sub_i32 s14, s0, s1
	s_cmp_gt_i32 s14, 23
	s_mov_b64 s[0:1], -1
	s_cbranch_scc0 .LBB0_1186
	s_add_i32 s0, s14, 0xffe8
	s_and_b32 s12, s0, 0xff
	s_mul_i32 s1, s12, 0xcd
	s_bfe_u32 s13, s1, 0x6000a
	s_mul_i32 s1, s13, 5
	s_sub_i32 s0, s0, s1
	s_and_b32 s0, s0, 0xff
	s_lshl_b32 s15, s0, 7
	s_lshl_b32 s16, s0, 8
	s_add_u32 s0, s21, s16
	s_addc_u32 s1, s22, 0
	s_add_u32 s50, s23, s16
	s_addc_u32 s51, s24, 0
	s_add_u32 s52, s25, s16
	s_getreg_b32 s17, hwreg(HW_REG_HW_ID, 0, 6)
	s_addc_u32 s53, s26, 0
	s_lshl_b32 s17, s17, 2
	s_and_b32 s17, s17, 0xfc
	s_add_i32 s17, s17, 0x20040
	v_mov_b32_e32 v0, s17
	ds_read_b32 v0, v0
	s_lshl_b32 s68, s13, 12
	v_mov_b64_e32 v[6:7], s[50:51]
	v_mov_b32_e32 v3, v1
	s_mul_i32 s13, s13, 0x9ffb00
	s_waitcnt lgkmcnt(0)
	v_readfirstlane_b32 s18, v0
	v_mov_b32_e32 v0, v1
	s_mov_b32 s16, 2
	v_mbcnt_lo_u32_b32 v0, -1, v0
	v_mbcnt_hi_u32_b32 v8, -1, v0
	v_lshl_or_b32 v0, s18, 6, v8
	v_bfe_u32 v9, v8, 4, 2
	v_readfirstlane_b32 s18, v0
	s_ashr_i32 s19, s18, 6
	s_lshl_b32 s18, s49, 8
	s_lshl_b32 s33, s19, 5
	s_add_i32 s54, s33, s18
	s_lshl_b32 s18, s19, 3
	v_or_b32_e32 v0, s18, v9
	s_lshl_b32 s56, s19, 1
	v_and_b32_e32 v13, 15, v8
	v_lshlrev_b32_e32 v20, 2, v9
	s_and_b32 s56, s56, 2
	v_lshl_add_u64 v[4:5], s[68:69], 0, v[0:1]
	v_bitop3_b32 v2, s56, v13, v20 bitop3:0x36
	v_mad_u64_u32 v[10:11], s[50:51], v4, s84, v[6:7]
	v_mad_u32_u24 v11, v5, s84, v11
	v_lshlrev_b32_e32 v2, 4, v2
	v_lshl_add_u64 v[16:17], v[10:11], 0, v[2:3]
	v_mov_b64_e32 v[10:11], s[52:53]
	v_mad_u64_u32 v[14:15], s[50:51], v4, s84, v[10:11]
	s_or_b32 s18, s18, 4
	v_mad_u32_u24 v15, v5, s84, v15
	v_or_b32_e32 v4, s18, v9
	v_mov_b32_e32 v5, v1
	v_lshl_add_u64 v[18:19], v[14:15], 0, v[2:3]
	s_bfe_u32 s18, s18, 0x20002
	v_lshl_add_u64 v[14:15], s[68:69], 0, v[4:5]
	s_lshl_b32 s33, s49, 2
	s_ashr_i32 s55, s54, 31
	v_bitop3_b32 v9, s18, v13, v20 bitop3:0x36
	v_mad_u64_u32 v[6:7], s[50:51], v14, s84, v[6:7]
	v_mad_u64_u32 v[10:11], s[50:51], v14, s84, v[10:11]
	s_ashr_i32 s18, s54, 6
	s_add_u32 s50, s68, s54
	s_addc_u32 s51, 0, s55
	s_lshl_b32 s19, s19, 11
	s_add_i32 s19, s19, 0
	v_mad_u32_u24 v7, v15, s84, v7
	v_lshlrev_b32_e32 v4, 4, v9
	s_mov_b32 m0, s19
	v_lshl_add_u64 v[6:7], v[6:7], 0, v[4:5]
	global_load_lds_dwordx4 v[16:17], off
	s_add_i32 m0, s19, 0x400
	v_mad_u32_u24 v11, v15, s84, v11
	global_load_lds_dwordx4 v[6:7], off
	s_add_i32 m0, s19, 0x4000
	v_lshl_add_u64 v[20:21], v[10:11], 0, v[4:5]
	global_load_lds_dwordx4 v[18:19], off
	s_add_i32 m0, s19, 0x4400
	v_lshl_add_u64 v[16:17], v[16:17], 0, s[60:61]
	global_load_lds_dwordx4 v[20:21], off
	s_add_i32 m0, s19, 0xa000
	v_lshl_add_u64 v[6:7], v[6:7], 0, s[60:61]
	global_load_lds_dwordx4 v[16:17], off
	s_add_i32 m0, s19, 0xa400
	v_and_b32_e32 v12, 31, v8
	global_load_lds_dwordx4 v[6:7], off
	v_lshl_add_u64 v[6:7], v[18:19], 0, s[60:61]
	s_add_i32 m0, s19, 0xe000
	v_or_b32_e32 v130, s50, v12
	global_load_lds_dwordx4 v[6:7], off
	v_lshl_add_u64 v[6:7], v[20:21], 0, s[60:61]
	s_add_i32 m0, s19, 0xe400
	v_bfe_u32 v9, v8, 5, 1
	global_load_lds_dwordx4 v[6:7], off
	v_mov_b64_e32 v[6:7], s[0:1]
	v_mad_u64_u32 v[6:7], s[0:1], v130, s84, v[6:7]
	v_mov_b32_e32 v16, 0xa00
	v_mad_i32_i24 v7, s51, v16, v7
	v_lshlrev_b32_e32 v16, 4, v9
	v_mov_b32_e32 v17, v1
	v_lshl_add_u64 v[6:7], v[6:7], 0, v[16:17]
	global_load_dwordx4 v[98:101], v[6:7], off
	global_load_dwordx4 v[102:105], v[6:7], off offset:32
	global_load_dwordx4 v[106:109], v[6:7], off offset:64
	global_load_dwordx4 v[110:113], v[6:7], off offset:96
	global_load_dwordx4 v[114:117], v[6:7], off offset:128
	global_load_dwordx4 v[118:121], v[6:7], off offset:160
	global_load_dwordx4 v[122:125], v[6:7], off offset:192
	global_load_dwordx4 v[126:129], v[6:7], off offset:224
	v_mov_b32_e32 v131, s51
	v_lshlrev_b64 v[6:7], 9, v[130:131]
	v_lshlrev_b32_e32 v22, 2, v8
	v_lshl_add_u64 v[16:17], s[6:7], 0, v[6:7]
	v_bfe_u32 v23, v8, 2, 2
	v_and_b32_e32 v22, 12, v22
	v_lshlrev_b32_e32 v141, 8, v12
	v_lshlrev_b32_e32 v12, 3, v8
	v_or_b32_e32 v24, v22, v23
	v_lshrrev_b32_e32 v10, 3, v8
	s_waitcnt vmcnt(0)
	global_load_dwordx2 v[132:133], v[16:17], off
	v_mov_b32_e32 v16, 0x4000
	v_and_or_b32 v142, v12, 8, v16
	v_bitop3_b32 v12, v22, v9, v23 bitop3:0x36
	v_lshlrev_b32_e32 v143, 4, v12
	v_bitop3_b32 v12, v9, v24, 2 bitop3:0x36
	v_lshlrev_b32_e32 v144, 4, v12
	v_bitop3_b32 v12, v9, v24, 4 bitop3:0x36
	v_lshlrev_b32_e32 v145, 4, v12
	v_bitop3_b32 v12, v9, v24, 6 bitop3:0x36
	v_lshlrev_b32_e32 v146, 4, v12
	v_bitop3_b32 v12, v9, v24, 8 bitop3:0x36
	v_lshlrev_b32_e32 v147, 4, v12
	v_bitop3_b32 v12, v9, v24, 10 bitop3:0x36
	v_and_b32_e32 v11, 2, v10
	v_bfe_u32 v13, v8, 1, 1
	v_lshlrev_b32_e32 v148, 4, v12
	v_bitop3_b32 v12, v9, v24, 12 bitop3:0x36
	v_lshlrev_b32_e32 v140, 2, v9
	v_or_b32_e32 v10, v13, v11
	v_lshlrev_b32_e32 v149, 4, v12
	v_bitop3_b32 v12, v9, v24, 14 bitop3:0x36
	v_or_b32_e32 v14, v140, v23
	v_bitop3_b32 v15, v13, v9, v11 bitop3:0x36
	v_bitop3_b32 v13, v9, v10, 2 bitop3:0x36
	v_lshlrev_b32_e32 v150, 4, v12
	v_and_b32_e32 v12, 12, v8
	v_lshlrev_b32_e32 v151, 8, v14
	v_or_b32_e32 v14, v15, v12
	v_or_b32_e32 v12, v13, v12
	v_or_b32_e32 v11, 2, v9
	v_lshlrev_b32_e32 v154, 4, v12
	v_bitop3_b32 v12, v8, 4, 12 bitop3:0x6c
	s_mov_b64 s[0:1], 0x2d990000
	s_add_i32 s33, s33, 4
	v_bitop3_b32 v13, v10, v12, v9 bitop3:0xde
	v_bitop3_b32 v12, v11, v12, v10 bitop3:0xde
	v_lshl_add_u64 v[134:135], v[6:7], 0, s[0:1]
	s_lshl_b32 s0, s12, 8
	v_lshlrev_b32_e32 v178, 4, v12
	v_bitop3_b32 v12, v8, 8, 12 bitop3:0x6c
	v_bitop3_b32 v8, v8, 12, v8 bitop3:0xc
	s_add_u32 s0, s0, s13
	v_lshlrev_b32_e32 v177, 4, v13
	v_bitop3_b32 v13, v10, v12, v9 bitop3:0xde
	v_bitop3_b32 v9, v10, v8, v9 bitop3:0xde
	v_bitop3_b32 v8, v11, v8, v10 bitop3:0xde
	s_addc_u32 s1, 0, 0
	v_lshlrev_b32_e32 v182, 4, v8
	v_or_b32_e32 v8, 4, v0
	v_mov_b64_e32 v[6:7], s[0:1]
	v_lshlrev_b32_e32 v181, 4, v9
	v_mad_u64_u32 v[8:9], s[0:1], v8, s84, v[6:7]
	v_lshlrev_b32_e32 v152, 4, v14
	v_bitop3_b32 v12, v11, v12, v10 bitop3:0xde
	v_lshl_add_u64 v[136:137], v[8:9], 0, v[4:5]
	v_mad_u64_u32 v[4:5], s[0:1], v0, s84, v[6:7]
	v_mov_b32_e32 v14, v1
	v_mov_b32_e32 v15, v1
	s_waitcnt vmcnt(0)
	s_waitcnt vmcnt(0) lgkmcnt(0)
	s_barrier
; #define WAIT_TILE(all_) do { if (all_) asm volatile("s_waitcnt vmcnt(0) lgkmcnt(0)" ::: "memory"); \
;         else if constexpr (MODE == 0) asm volatile("s_waitcnt vmcnt(5) lgkmcnt(0)" ::: "memory"); else asm volatile("s_waitcnt vmcnt(4) lgkmcnt(0)" ::: "memory"); \
;         __builtin_amdgcn_s_barrier(); asm volatile("" ::: "memory"); } while (0)
; template <int MODE>
; __device__ __forceinline__ void attn_unit(LAS char* lds, const AttnPtrs& A, int b, int qb) {
;     ...
;     f32x16 o1[4];
; #pragma unroll
;     for (int c = 0; c < 4; ++c) o1[c] = f32x16{};
;     float m1 = -1e30f, l1 = 0.f;
;     unsigned long long mw_next = 0ull;
;     if constexpr (MODE == 1) { mw_next = A.MASK[qrow * 64]; asm volatile("" : "+v"(mw_next)); }
;     bf16x8 pk[4]; float a1 = 1.f;
;     ...
;     WAIT_TILE(true);
;     int st_cur = 0, st_nn = 2;
;     for (int t = 0; t < NT; ++t) {
;         unsigned mlo = 0, mhi = 0;
;         if constexpr (MODE == 1) { if (t <= cw) {
;             const unsigned long long w = mw_next; mlo = (unsigned)w >> (4 * hi); mhi = (unsigned)(w >> 32) >> (4 * hi);
;             asm volatile("" : "+v"(mlo), "+v"(mhi));
;             if (t < cw) { const unsigned long long* mp_ = A.MASK + qrow * 64 + t + 1; asm volatile("global_load_dwordx2 %0, %1, off" : "+v"(mw_next) : "v"(mp_) : "memory"); } } }
;         const bool more2 = (t + 2 < NT);
;         if (more2) STAGE(t + 2, st_nn);
;         if (t <= cw) {
	v_lshlrev_b32_e32 v179, 4, v13
	v_lshlrev_b32_e32 v180, 4, v12
	v_lshl_add_u64 v[138:139], v[4:5], 0, v[2:3]
	v_mov_b32_e32 v0, v1
	v_mov_b32_e32 v2, v1
	v_mov_b32_e32 v4, v1
	v_mov_b32_e32 v5, v1
	v_mov_b32_e32 v6, v1
	v_mov_b32_e32 v7, v1
	v_mov_b32_e32 v8, v1
	v_mov_b32_e32 v9, v1
	v_mov_b32_e32 v10, v1
	v_mov_b32_e32 v11, v1
	v_mov_b32_e32 v12, v1
	v_mov_b32_e32 v13, v1
	v_mov_b64_e32 v[64:65], v[14:15]
	v_mov_b64_e32 v[48:49], v[14:15]
	v_mov_b64_e32 v[32:33], v[14:15]
	v_mov_b64_e32 v[62:63], v[12:13]
	v_mov_b64_e32 v[60:61], v[10:11]
	v_mov_b64_e32 v[58:59], v[8:9]
	v_mov_b64_e32 v[56:57], v[6:7]
	v_mov_b64_e32 v[54:55], v[4:5]
	v_mov_b64_e32 v[52:53], v[2:3]
	v_mov_b64_e32 v[50:51], v[0:1]
	v_mov_b64_e32 v[46:47], v[12:13]
	v_mov_b64_e32 v[44:45], v[10:11]
	v_mov_b64_e32 v[42:43], v[8:9]
	v_mov_b64_e32 v[40:41], v[6:7]
	v_mov_b64_e32 v[38:39], v[4:5]
	v_mov_b64_e32 v[36:37], v[2:3]
	v_mov_b64_e32 v[34:35], v[0:1]
	v_mov_b64_e32 v[30:31], v[12:13]
	v_mov_b64_e32 v[28:29], v[10:11]
	v_mov_b64_e32 v[26:27], v[8:9]
	v_mov_b64_e32 v[24:25], v[6:7]
	v_mov_b64_e32 v[22:23], v[4:5]
	v_mov_b64_e32 v[20:21], v[2:3]
	v_mov_b64_e32 v[18:19], v[0:1]
	v_mov_b64_e32 v[16:17], v[14:15]
	s_mov_b32 s17, 0
	v_or_b32_e32 v153, 0x800, v151
	v_or_b32_e32 v155, 0x1000, v151
	v_or_b32_e32 v156, 0x1800, v151
	v_or_b32_e32 v157, 0x2000, v151
	v_or_b32_e32 v158, 0x2800, v151
	v_or_b32_e32 v159, 0x3000, v151
	v_or_b32_e32 v176, 0x3800, v151
	v_mov_b32_e32 v184, 0xf149f2ca
	v_mov_b32_e32 v253, s97
	v_mov_b32_e32 v252, 0
	v_mov_b64_e32 v[236:237], 0
	v_mov_b64_e32 v[238:239], 0
	v_mov_b64_e32 v[240:241], 0
	v_mov_b64_e32 v[242:243], 0
	v_mov_b64_e32 v[244:245], 0
	v_mov_b64_e32 v[246:247], 0
	v_mov_b64_e32 v[248:249], 0
	v_mov_b64_e32 v[250:251], 0
	v_mov_b32_e32 v183, 0
	v_mov_b64_e32 v[14:15], v[12:13]
	v_mov_b64_e32 v[12:13], v[10:11]
	v_mov_b64_e32 v[10:11], v[8:9]
	v_mov_b64_e32 v[8:9], v[6:7]
	v_mov_b64_e32 v[6:7], v[4:5]
	v_mov_b64_e32 v[4:5], v[2:3]
	v_mov_b64_e32 v[2:3], v[0:1]
	s_mov_b32 s50, 0
	s_cmp_le_i32 s50, s18
	s_cselect_b64 s[12:13], -1, 0
	s_cmp_gt_i32 s50, s18
	s_cbranch_scc1 .LBB0_1171
	s_branch .LBB0_1172

; __device__ __forceinline__ float max_x32(float v) { const unsigned u = __float_as_uint(v); auto r = __builtin_amdgcn_permlane32_swap(u, u, false, false); return fmaxf(__uint_as_float(r[0]), __uint_as_float(r[1])); }
; template <bool MASKED>
; __device__ __forceinline__ void softmax_tile(f32x16& s0, f32x16& s1, float& m, float& l, float& alpha, unsigned mlo, unsigned mhi, bf16x8 (&pk)[4]) {
;     ...
;     if (MASKED) {
; #pragma unroll
;         for (int r = 0; r < 16; ++r) { const int bit = (r & 3) + 8 * (r >> 2); if (!((mlo >> bit) & 1u)) s0[r] = NEG; if (!((mhi >> bit) & 1u)) s1[r] = NEG; }
;     }
;     float mx = fmaxf(s0[0], s1[0]);
; #pragma unroll
;     for (int r = 1; r < 16; ++r) mx = fmaxf(mx, fmaxf(s0[r], s1[r]));
;     mx = max_x32(mx);
;     const float mn = fmaxf(m, mx);
;     alpha = __builtin_amdgcn_exp2f(m - mn); m = mn;
.LBB0_1176:
	s_andn2_b64 vcc, exec, s[12:13]
	s_cbranch_vccnz .LBB0_1180
	s_mul_i32 s12, s17, 0xa000
	s_add_i32 s12, s12, 0
	v_add_u32_e32 v194, s12, v141
	v_add_u32_e32 v70, v194, v143
	v_add_u32_e32 v74, v194, v144
	ds_read_b128 v[66:69], v70
	ds_read_b128 v[70:73], v70 offset:8192
	ds_read_b128 v[160:163], v74
	ds_read_b128 v[164:167], v74 offset:8192
	v_add_u32_e32 v74, v194, v145
	ds_read_b128 v[168:171], v74
	ds_read_b128 v[172:175], v74 offset:8192
	v_add_u32_e32 v74, v194, v146
	ds_read_b128 v[186:189], v74 offset:8192
	ds_read_b128 v[190:193], v74
	s_waitcnt lgkmcnt(0)
	v_mfma_f32_32x32x16_bf16 v[82:97], v[66:69], v[98:101], v[236:251]
	v_mfma_f32_32x32x16_bf16 v[66:81], v[70:73], v[98:101], v[236:251]
	v_mfma_f32_32x32x16_bf16 v[82:97], v[160:163], v[102:105], v[82:97]
	v_mfma_f32_32x32x16_bf16 v[66:81], v[164:167], v[102:105], v[66:81]
	v_mfma_f32_32x32x16_bf16 v[82:97], v[168:171], v[106:109], v[82:97]
	v_mfma_f32_32x32x16_bf16 v[66:81], v[172:175], v[106:109], v[66:81]
	v_mfma_f32_32x32x16_bf16 v[82:97], v[190:193], v[110:113], v[82:97]
	v_mfma_f32_32x32x16_bf16 v[66:81], v[186:189], v[110:113], v[66:81]
	v_add_u32_e32 v164, v194, v147
	v_add_u32_e32 v172, v194, v148
	v_add_u32_e32 v190, v194, v149
	v_add_u32_e32 v198, v194, v150
	ds_read_b128 v[160:163], v164
	ds_read_b128 v[164:167], v164 offset:8192
	ds_read_b128 v[168:171], v172
	ds_read_b128 v[172:175], v172 offset:8192
	ds_read_b128 v[186:189], v190
	ds_read_b128 v[190:193], v190 offset:8192
	ds_read_b128 v[194:197], v198 offset:8192
	ds_read_b128 v[206:209], v198
	s_waitcnt lgkmcnt(0)
	v_mfma_f32_32x32x16_bf16 v[82:97], v[160:163], v[114:117], v[82:97]
	v_mfma_f32_32x32x16_bf16 v[66:81], v[164:167], v[114:117], v[66:81]
	v_mfma_f32_32x32x16_bf16 v[82:97], v[168:171], v[118:121], v[82:97]
	v_mfma_f32_32x32x16_bf16 v[66:81], v[172:175], v[118:121], v[66:81]
	v_mfma_f32_32x32x16_bf16 v[82:97], v[186:189], v[122:125], v[82:97]
	v_mfma_f32_32x32x16_bf16 v[66:81], v[190:193], v[122:125], v[66:81]
	v_mfma_f32_32x32x16_bf16 v[82:97], v[206:209], v[126:129], v[82:97]
	v_mfma_f32_32x32x16_bf16 v[66:81], v[194:197], v[126:129], v[66:81]
	v_bfe_i32 v160, v185, 0, 1
	v_bfe_i32 v161, v185, 1, 1
	v_bfe_i32 v162, v185, 2, 1
	v_bfe_i32 v163, v185, 3, 1
	v_bfe_i32 v164, v185, 8, 1
	v_bfe_i32 v165, v185, 9, 1
	v_bfe_i32 v166, v185, 10, 1
	v_bfe_i32 v167, v185, 11, 1
	v_bfe_i32 v168, v185, 16, 1
	v_bfe_i32 v169, v185, 17, 1
	v_bfe_i32 v170, v185, 18, 1
	v_bfe_i32 v171, v185, 19, 1
	v_bfe_i32 v172, v185, 24, 1
	v_bfe_i32 v173, v185, 25, 1
	v_bfe_i32 v174, v185, 26, 1
	v_bfe_i32 v175, v185, 27, 1
	v_bfe_i32 v186, v0, 0, 1
	v_bfe_i32 v187, v0, 1, 1
	v_bfe_i32 v188, v0, 2, 1
	v_bfe_i32 v189, v0, 3, 1
	v_bfe_i32 v190, v0, 8, 1
	v_bfe_i32 v191, v0, 9, 1
	v_bfe_i32 v192, v0, 10, 1
	v_bfe_i32 v193, v0, 11, 1
	v_bfe_i32 v194, v0, 16, 1
	v_bfe_i32 v195, v0, 17, 1
	v_bfe_i32 v196, v0, 18, 1
	v_bfe_i32 v197, v0, 19, 1
	v_bfe_i32 v198, v0, 24, 1
	v_bfe_i32 v199, v0, 25, 1
	v_bfe_i32 v206, v0, 26, 1
	v_bfe_i32 v207, v0, 27, 1
	v_bfi_b32 v82, v160, v82, v215
	v_bfi_b32 v83, v161, v83, v215
	v_bfi_b32 v84, v162, v84, v215
	v_bfi_b32 v85, v163, v85, v215
	v_bfi_b32 v86, v164, v86, v215
	v_bfi_b32 v87, v165, v87, v215
	v_bfi_b32 v88, v166, v88, v215
	v_bfi_b32 v89, v167, v89, v215
	v_bfi_b32 v90, v168, v90, v215
	v_bfi_b32 v91, v169, v91, v215
	v_bfi_b32 v92, v170, v92, v215
	v_bfi_b32 v93, v171, v93, v215
	v_bfi_b32 v94, v172, v94, v215
	v_bfi_b32 v95, v173, v95, v215
	v_bfi_b32 v96, v174, v96, v215
	v_bfi_b32 v97, v175, v97, v215
	v_bfi_b32 v66, v186, v66, v215
	v_bfi_b32 v67, v187, v67, v215
	v_bfi_b32 v68, v188, v68, v215
	v_bfi_b32 v69, v189, v69, v215
	v_bfi_b32 v70, v190, v70, v215
	v_bfi_b32 v71, v191, v71, v215
	v_bfi_b32 v72, v192, v72, v215
	v_bfi_b32 v73, v193, v73, v215
	v_bfi_b32 v74, v194, v74, v215
	v_bfi_b32 v75, v195, v75, v215
	v_bfi_b32 v76, v196, v76, v215
	v_bfi_b32 v77, v197, v77, v215
	v_bfi_b32 v78, v198, v78, v215
	v_bfi_b32 v79, v199, v79, v215
	v_bfi_b32 v80, v206, v80, v215
	v_bfi_b32 v81, v207, v81, v215
	v_max3_f32 v160, v82, v83, v84
	v_max3_f32 v161, v85, v86, v87
	v_max3_f32 v162, v88, v89, v90
	v_max3_f32 v163, v91, v92, v93
	v_max3_f32 v164, v94, v95, v96
	v_max3_f32 v165, v97, v66, v67
	v_max3_f32 v166, v68, v69, v70
	v_max3_f32 v167, v71, v72, v73
	v_max3_f32 v168, v74, v75, v76
	v_max3_f32 v169, v77, v78, v79
	v_max3_f32 v160, v160, v161, v162
	v_max3_f32 v163, v163, v164, v165
	v_max3_f32 v166, v166, v167, v168
	v_max3_f32 v169, v169, v80, v81
	v_max3_f32 v160, v160, v163, v166
	v_max_f32_e32 v160, v160, v169
	v_mov_b32_e32 v161, v160
	s_nop 1
	v_permlane32_swap_b32_e32 v160, v161
	v_max_f32_e32 v160, v160, v161
	v_mov_b32_e32 v0, 1.0
	v_mov_b32_e32 v162, v184
	v_cmp_lt_f32_e32 vcc, v253, v160
	s_cbranch_vccz .Lm1_cfast
	v_add_f32_e32 v161, v160, v252
	v_cndmask_b32_e32 v162, v184, v161, vcc
	v_sub_f32_e32 v161, v162, v252
	v_cndmask_b32_e32 v161, 0, v161, vcc
	v_mov_b32_e32 v160, 0x41000000
	v_cndmask_b32_e32 v253, v253, v160, vcc
	v_cndmask_b32_e32 v252, v252, v162, vcc
	v_sub_f32_e32 v0, v184, v162
	v_exp_f32_e32 v0, v0
	v_sub_f32_e32 v82, v82, v161
	v_sub_f32_e32 v83, v83, v161
	v_sub_f32_e32 v84, v84, v161
	v_sub_f32_e32 v85, v85, v161
	v_sub_f32_e32 v86, v86, v161
	v_sub_f32_e32 v87, v87, v161
	v_sub_f32_e32 v88, v88, v161
	v_sub_f32_e32 v89, v89, v161
	v_sub_f32_e32 v90, v90, v161
	v_sub_f32_e32 v91, v91, v161
	v_sub_f32_e32 v92, v92, v161
	v_sub_f32_e32 v93, v93, v161
	v_sub_f32_e32 v94, v94, v161
	v_sub_f32_e32 v95, v95, v161
	v_sub_f32_e32 v96, v96, v161
	v_sub_f32_e32 v97, v97, v161
	v_sub_f32_e32 v66, v66, v161
	v_sub_f32_e32 v67, v67, v161
	v_sub_f32_e32 v68, v68, v161
	v_sub_f32_e32 v69, v69, v161
	v_sub_f32_e32 v70, v70, v161
	v_sub_f32_e32 v71, v71, v161
	v_sub_f32_e32 v72, v72, v161
	v_sub_f32_e32 v73, v73, v161
	v_sub_f32_e32 v74, v74, v161
	v_sub_f32_e32 v75, v75, v161
	v_sub_f32_e32 v76, v76, v161
	v_sub_f32_e32 v77, v77, v161
	v_sub_f32_e32 v78, v78, v161
	v_sub_f32_e32 v79, v79, v161
	v_sub_f32_e32 v80, v80, v161
	v_sub_f32_e32 v81, v81, v161
	v_sub_f32_e32 v236, 0, v252
	v_sub_f32_e32 v237, 0, v252
	v_sub_f32_e32 v238, 0, v252
	v_sub_f32_e32 v239, 0, v252
	v_sub_f32_e32 v240, 0, v252
	v_sub_f32_e32 v241, 0, v252
	v_sub_f32_e32 v242, 0, v252
	v_sub_f32_e32 v243, 0, v252
	v_sub_f32_e32 v244, 0, v252
	v_sub_f32_e32 v245, 0, v252
	v_sub_f32_e32 v246, 0, v252
	v_sub_f32_e32 v247, 0, v252
	v_sub_f32_e32 v248, 0, v252
	v_sub_f32_e32 v249, 0, v252
	v_sub_f32_e32 v250, 0, v252
	v_sub_f32_e32 v251, 0, v252

; #define LAS __attribute__((address_space(3)))
; template <int MODE>
; __device__ __forceinline__ void attn_unit(LAS char* lds, const AttnPtrs& A, int b, int qb) {
;     ...
;     const int tid = opaque_tid(), lane = tid & 63, r32 = lane & 31, hi = lane >> 5, wid = __builtin_amdgcn_readfirstlane(tid >> 6);
;     const int strm = (MODE == 2) ? (wid & 1) : 0;
;     const size_t rowbase = (size_t)b * SEQ; const int q0 = (MODE == 2) ? qb * 128 + (wid >> 1) * 32 : qb * 256 + wid * 32; const int cw = q0 >> 6, NT = (MODE == 2) ? 2 * qb + 2 : 4 * qb + 4;
;     const size_t qrow = rowbase + q0 + r32;
;     const bf16_t* ksrc[2]; const bf16_t* vsrc[2];
; #pragma unroll
;     for (int i = 0; i < 2; ++i) { const unsigned row = 4u * (2 * wid + i) + (lane >> 4), ch = (lane & 15) ^ (((row & 3) << 2) | ((row >> 2) & 3));
;         ksrc[i] = A.K + (rowbase + row) * A.ldk + ch * 8; vsrc[i] = A.V + (rowbase + row) * A.ldv + ch * 8; }
;     const bf16_t* k64src = nullptr;
;     if constexpr (MODE == 0) { const unsigned row = 8u * wid + (lane >> 3), ch = (lane & 7) ^ ((row >> 1) & 7); k64src = A.K64 + (rowbase + row) * 64 + ch * 8; }
;     const unsigned fK = ((r32 & 3) << 2) | ((r32 >> 2) & 3);
;     const unsigned g64 = (r32 >> 1) & 7;
;     const int q4 = (lane & 15) >> 2, p4 = lane & 3, blk = (lane >> 4) & 1;
;     unsigned vrow[2], vlow[2];
; #pragma unroll
;     for (int t = 0; t < 2; ++t) { vrow[t] = 4 * hi + 8 * t + q4; vlow[t] = (unsigned)((2 * blk + (p4 >> 1)) ^ ((hi + 2 * t) & 3)); }
;     ...
;     STAGE(0, 0); STAGE(1, 1);
;     bf16x8 qf[NQ];
; #pragma unroll
;     for (int s = 0; s < NQ; ++s) qf[s] = *(const bf16x8*)(A.Q + qrow * A.ldq + 64 * strm + 16 * s + 8 * hi);
;     if constexpr (MODE == 0) {
; #pragma unroll
;         for (int s = 0; s < 4; ++s) {
;             const u32x4 w = __builtin_bit_cast(u32x4, qf[8 + s]);
;             const f32x4 t0 = *(const f32x4*)(A.subg + (qrow * 56 + 8 * s + 4 * hi) * 2), t1 = *(const f32x4*)(A.subg + (qrow * 56 + 8 * s + 4 * hi) * 2 + 4);
;             u32x4 o;
;     ...
;                 const int qb = 15 - it / 44, w = it % 44;
;                 if (w < 24) { const int b = w / 6, h = w % 6;
;                     att::AttnPtrs A{QMLA + h * 192, NUQ, KMLA + h * 128, 768, KROPE, VMLA + h * 128, 768, GATE + h * 128, GATE + h * 128, nullptr, 0.f, 0.f, (const float*)TAB};
;     ...
;                     att::attn_unit<0>((LAS char*)lds, A, b, qb);
.LBB0_1186:
	s_and_b64 vcc, exec, s[0:1]
	s_cbranch_vccz .LBB0_1201
	s_bfe_i32 s0, s14, 0x80000
	s_mul_i32 s0, s0, 43
	s_bfe_u32 s1, s0, 0x1000f
	s_bfe_u32 s0, s0, 0x80008
	s_add_i32 s12, s0, s1
	s_mul_i32 s0, s12, 6
	s_sub_i32 s0, s14, s0
	s_sext_i32_i8 s13, s0
	s_mul_i32 s0, s13, 0xc0
	s_ashr_i32 s1, s0, 31
	s_lshl_b64 s[0:1], s[0:1], 1
	s_add_u32 s16, s29, s0
	s_addc_u32 s17, s34, s1
	s_lshl_b32 s0, s13, 7
	s_ashr_i32 s1, s0, 31
	s_lshl_b64 s[0:1], s[0:1], 1
	s_add_u32 s52, s35, s0
	s_addc_u32 s53, s44, s1
	s_add_u32 s54, s45, s0
	s_getreg_b32 s13, hwreg(HW_REG_HW_ID, 0, 6)
	s_addc_u32 s55, s46, s1
	s_lshl_b32 s13, s13, 2
	s_and_b32 s13, s13, 0xfc
	s_add_i32 s13, s13, 0x20040
	v_mov_b32_e32 v0, s13
	ds_read_b32 v0, v0
	s_lshl_b32 s51, s49, 8
	v_mov_b64_e32 v[6:7], s[52:53]
	v_mov_b32_e32 v3, v1
	s_mov_b32 s33, 2
	s_waitcnt lgkmcnt(0)
	v_readfirstlane_b32 s13, v0
	v_mov_b32_e32 v0, v1
	s_mov_b32 s50, 0
	v_mbcnt_lo_u32_b32 v0, -1, v0
	v_mbcnt_hi_u32_b32 v8, -1, v0
	v_lshl_or_b32 v11, s13, 6, v8
	v_bfe_u32 v10, v8, 4, 2
	v_readfirstlane_b32 s13, v11
	s_ashr_i32 s13, s13, 6
	s_bfe_i64 s[14:15], s[12:13], 0x80000
	s_lshl_b32 s56, s13, 5
	s_lshl_b32 s58, s13, 3
	s_lshl_b64 s[18:19], s[14:15], 12
	s_add_i32 s56, s56, s51
	s_lshl_b32 s51, s49, 2
	v_or_b32_e32 v0, s58, v10
	s_lshl_b32 s49, s13, 1
	v_and_b32_e32 v16, 15, v8
	v_lshlrev_b32_e32 v17, 2, v10
	s_and_b32 s49, s49, 2
	v_lshl_add_u64 v[4:5], s[18:19], 0, v[0:1]
	v_bitop3_b32 v2, s49, v16, v17 bitop3:0x36
	v_mad_u64_u32 v[12:13], s[52:53], v4, s20, v[6:7]
	v_mad_i32_i24 v13, v5, s20, v13
	v_lshlrev_b32_e32 v2, 4, v2
	v_lshl_add_u64 v[38:39], v[12:13], 0, v[2:3]
	v_mov_b64_e32 v[12:13], s[54:55]
	v_mad_u64_u32 v[14:15], s[52:53], v4, s20, v[12:13]
	s_or_b32 s49, s58, 4
	v_mad_i32_i24 v15, v5, s20, v15
	v_or_b32_e32 v4, s49, v10
	v_mov_b32_e32 v5, v1
	v_lshl_add_u64 v[40:41], v[14:15], 0, v[2:3]
	s_bfe_u32 s49, s49, 0x20002
	v_lshl_add_u64 v[14:15], s[18:19], 0, v[4:5]
	v_bitop3_b32 v10, s49, v16, v17 bitop3:0x36
	v_mad_u64_u32 v[6:7], s[52:53], v14, s20, v[6:7]
	v_mad_i32_i24 v7, v15, s20, v7
	v_lshlrev_b32_e32 v4, 4, v10
	s_ashr_i32 s57, s56, 31
	v_lshl_add_u64 v[42:43], v[6:7], 0, v[4:5]
	v_mad_u64_u32 v[6:7], s[52:53], v14, s20, v[12:13]
	s_ashr_i32 s49, s56, 6
	v_and_b32_e32 v9, 31, v8
	s_add_u32 s52, s18, s56
	v_mad_i32_i24 v7, v15, s20, v7
	v_or_b32_e32 v178, s52, v9
	v_mov_b64_e32 v[14:15], s[16:17]
	s_movk_i32 s16, 0x900
	v_mad_u64_u32 v[14:15], s[16:17], v178, s16, v[14:15]
	v_mad_u64_u32 v[18:19], s[16:17], v178, 56, 0
	v_lshl_add_u64 v[50:51], v[6:7], 0, v[4:5]
	v_bfe_u32 v12, v8, 5, 1
	s_addc_u32 s53, s19, s57
	v_mov_b32_e32 v7, 0x900
	v_mov_b32_e32 v20, v19
	v_lshlrev_b32_e32 v176, 2, v12
	v_mad_i32_i24 v15, s53, v7, v15
	v_lshlrev_b32_e32 v16, 4, v12
	v_mov_b32_e32 v17, v1
	v_mad_u64_u32 v[20:21], s[16:17], s53, 56, v[20:21]
	v_lshl_add_u64 v[52:53], v[14:15], 0, v[16:17]
	v_or_b32_e32 v18, v18, v176
	v_mov_b32_e32 v19, v20
	global_load_dwordx4 v[14:17], v[52:53], off offset:256
	v_lshl_add_u64 v[58:59], v[18:19], 3, s[10:11]
	global_load_dwordx4 v[18:21], v[58:59], off offset:16
	global_load_dwordx4 v[22:25], v[58:59], off
	v_bfe_u32 v6, v8, 3, 3
	v_or_b32_e32 v6, s58, v6
	v_lshrrev_b32_e32 v10, 1, v6
	v_mov_b32_e32 v7, v1
	s_lshl_b32 s16, s13, 11
	v_xor_b32_e32 v13, v10, v8
	v_lshl_add_u64 v[26:27], s[18:19], 0, v[6:7]
	v_lshrrev_b32_e32 v28, 3, v8
	s_add_i32 s16, s16, 0
	v_lshlrev_b64 v[26:27], 7, v[26:27]
	v_and_b32_e32 v28, 2, v28
	v_bfe_u32 v29, v11, 1, 1
	v_or_b32_e32 v67, 2, v12
	v_lshlrev_b32_e32 v13, 4, v13
	s_mov_b32 m0, s16
	v_lshlrev_b32_e32 v30, 2, v8
	v_or_b32_e32 v64, v29, v28
	v_bitop3_b32 v66, v29, v12, v28 bitop3:0x36
	v_bitop3_b32 v68, v29, v67, v28 bitop3:0x36
	v_lshl_add_u64 v[26:27], s[8:9], 0, v[26:27]
	v_and_b32_e32 v28, 0x70, v13
	v_mov_b32_e32 v29, v1
	global_load_lds_dwordx4 v[38:39], off
	v_lshl_add_u64 v[54:55], v[26:27], 0, v[28:29]
	v_and_b32_e32 v13, 12, v30
	global_load_dwordx4 v[26:29], v[52:53], off offset:288
	global_load_dwordx4 v[30:33], v[58:59], off offset:80
	global_load_dwordx4 v[34:37], v[58:59], off offset:64
	s_add_i32 m0, s16, 0x400
	s_lshl_b32 s13, s13, 10
	global_load_lds_dwordx4 v[42:43], off
	s_add_i32 m0, s16, 0x4000
	s_sub_i32 s17, s16, s13
	global_load_lds_dwordx4 v[40:41], off
	s_add_i32 m0, s16, 0x4400
	v_lshl_add_u64 v[38:39], v[38:39], 0, s[94:95]
	global_load_lds_dwordx4 v[50:51], off
	s_add_i32 m0, s17, 0x8000
	v_lshl_add_u64 v[56:57], v[40:41], 0, s[94:95]
	global_load_lds_dwordx4 v[54:55], off
	s_add_i32 m0, s16, 0xa000
	v_lshl_add_u64 v[50:51], v[50:51], 0, s[94:95]
	global_load_lds_dwordx4 v[38:39], off
	v_lshl_add_u64 v[38:39], v[42:43], 0, s[94:95]
	s_add_i32 m0, s16, 0xa400
	v_bfe_u32 v62, v8, 2, 2
	global_load_lds_dwordx4 v[38:39], off
	global_load_dwordx4 v[38:41], v[52:53], off offset:320
	s_nop 0
	global_load_dwordx4 v[42:45], v[58:59], off offset:144
	global_load_dwordx4 v[46:49], v[58:59], off offset:128
	s_add_i32 m0, s16, 0xe000
	v_lshlrev_b32_e32 v177, 7, v9
	global_load_lds_dwordx4 v[56:57], off
	s_add_i32 m0, s16, 0xe400
	v_lshlrev_b32_e32 v186, 8, v9
	global_load_lds_dwordx4 v[50:51], off
	v_lshl_add_u64 v[50:51], v[54:55], 0, s[38:39]
	s_add_i32 m0, s17, 0x12000
	v_lshlrev_b32_e32 v9, 3, v8
	global_load_lds_dwordx4 v[50:51], off
	global_load_dwordx4 v[112:115], v[52:53], off
	global_load_dwordx4 v[116:119], v[52:53], off offset:32
	global_load_dwordx4 v[120:123], v[52:53], off offset:64
	global_load_dwordx4 v[124:127], v[52:53], off offset:96
	global_load_dwordx4 v[128:131], v[52:53], off offset:128
	global_load_dwordx4 v[132:135], v[52:53], off offset:160
	global_load_dwordx4 v[136:139], v[52:53], off offset:192
	global_load_dwordx4 v[140:143], v[52:53], off offset:224
	s_nop 0
	global_load_dwordx4 v[50:53], v[52:53], off offset:352
	v_or_b32_e32 v69, v13, v62
	v_lshrrev_b32_e32 v63, 1, v11
	v_bfe_u32 v11, v11, 1, 3
	s_add_i32 s17, s51, 4
	s_add_i32 s18, s13, 0
	s_lshl_b64 s[14:15], s[14:15], 19
	s_add_u32 s14, s14, 0x1b914000
	s_addc_u32 s15, s15, 0
	v_lshlrev_b64 v[6:7], 7, v[6:7]
	v_lshl_add_u64 v[180:181], s[14:15], 0, v[6:7]
	s_waitcnt vmcnt(0)
; __device__ __forceinline__ unsigned cvtpk(float lo, float hi) { unsigned r; asm("v_cvt_pk_bf16_f32 %0, %1, %2" : "=v"(r) : "v"(lo), "v"(hi)); return r; }
; __device__ __forceinline__ float bf_lo(unsigned w) { return __uint_as_float(w << 16); }
; __device__ __forceinline__ float bf_hi(unsigned w) { return __uint_as_float(w & 0xffff0000u); }
; template <int MODE>
; __device__ __forceinline__ void attn_unit(LAS char* lds, const AttnPtrs& A, int b, int qb) {
;     ...
;     if constexpr (MODE == 0) {
; #pragma unroll
;         for (int s = 0; s < 4; ++s) {
;             const u32x4 w = __builtin_bit_cast(u32x4, qf[8 + s]);
;             const f32x4 t0 = *(const f32x4*)(A.subg + (qrow * 56 + 8 * s + 4 * hi) * 2), t1 = *(const f32x4*)(A.subg + (qrow * 56 + 8 * s + 4 * hi) * 2 + 4);
;             u32x4 o;
;             { const float a = bf_lo(w.x), b = bf_hi(w.x); o.x = cvtpk(a * t0[0] - b * t0[1], b * t0[0] + a * t0[1]); }
;             { const float a = bf_lo(w.y), b = bf_hi(w.y); o.y = cvtpk(a * t0[2] - b * t0[3], b * t0[2] + a * t0[3]); }
;             { const float a = bf_lo(w.z), b = bf_hi(w.z); o.z = cvtpk(a * t1[0] - b * t1[1], b * t1[0] + a * t1[1]); }
;             { const float a = bf_lo(w.w), b = bf_hi(w.w); o.w = cvtpk(a * t1[2] - b * t1[3], b * t1[2] + a * t1[3]); }
;             qf[8 + s] = __builtin_bit_cast(bf16x8, o);
;         }
;     }
; #pragma unroll
;     for (int s = 0; s < NQ; ++s) asm volatile("" :: "v"(qf[s]));
	v_lshlrev_b32_e32 v54, 16, v14
	v_and_b32_e32 v55, 0xffff0000, v14
	v_pk_mul_f32 v[56:57], v[22:23], v[54:55]
	v_pk_mul_f32 v[22:23], v[22:23], v[54:55] op_sel:[0,1] op_sel_hi:[1,0]
	v_sub_f32_e32 v14, v56, v57
	global_load_dwordx4 v[54:57], v[58:59], off offset:208
	s_nop 0
	global_load_dwordx4 v[58:61], v[58:59], off offset:192
	v_add_f32_e32 v22, v22, v23
	v_cvt_pk_bf16_f32 v144, v14, v22
	v_lshlrev_b32_e32 v14, 16, v15
	v_and_b32_e32 v15, 0xffff0000, v15
	v_pk_mul_f32 v[22:23], v[24:25], v[14:15]
	v_pk_mul_f32 v[14:15], v[24:25], v[14:15] op_sel:[0,1] op_sel_hi:[1,0]
	v_sub_f32_e32 v22, v22, v23
	v_add_f32_e32 v14, v14, v15
	v_cvt_pk_bf16_f32 v145, v22, v14
	v_lshlrev_b32_e32 v14, 16, v16
	v_and_b32_e32 v15, 0xffff0000, v16
	v_pk_mul_f32 v[22:23], v[18:19], v[14:15]
	v_pk_mul_f32 v[14:15], v[18:19], v[14:15] op_sel:[0,1] op_sel_hi:[1,0]
	v_sub_f32_e32 v16, v22, v23
	v_add_f32_e32 v14, v14, v15
	v_cvt_pk_bf16_f32 v146, v16, v14
	v_lshlrev_b32_e32 v14, 16, v17
	v_and_b32_e32 v15, 0xffff0000, v17
	v_pk_mul_f32 v[16:17], v[20:21], v[14:15]
	v_pk_mul_f32 v[14:15], v[20:21], v[14:15] op_sel:[0,1] op_sel_hi:[1,0]
	v_sub_f32_e32 v16, v16, v17
	v_add_f32_e32 v14, v14, v15
	v_cvt_pk_bf16_f32 v147, v16, v14
	v_lshlrev_b32_e32 v14, 16, v26
	v_and_b32_e32 v15, 0xffff0000, v26
	v_pk_mul_f32 v[16:17], v[34:35], v[14:15]
	v_pk_mul_f32 v[14:15], v[34:35], v[14:15] op_sel:[0,1] op_sel_hi:[1,0]
	v_sub_f32_e32 v16, v16, v17
	v_add_f32_e32 v14, v14, v15
	v_cvt_pk_bf16_f32 v148, v16, v14
	v_lshlrev_b32_e32 v14, 16, v27
	v_and_b32_e32 v15, 0xffff0000, v27
	v_pk_mul_f32 v[16:17], v[36:37], v[14:15]
	v_pk_mul_f32 v[14:15], v[36:37], v[14:15] op_sel:[0,1] op_sel_hi:[1,0]
	v_sub_f32_e32 v16, v16, v17
	v_add_f32_e32 v14, v14, v15
	v_cvt_pk_bf16_f32 v149, v16, v14
	v_lshlrev_b32_e32 v14, 16, v28
	v_and_b32_e32 v15, 0xffff0000, v28
	v_pk_mul_f32 v[16:17], v[30:31], v[14:15]
	v_pk_mul_f32 v[14:15], v[30:31], v[14:15] op_sel:[0,1] op_sel_hi:[1,0]
	v_sub_f32_e32 v16, v16, v17
	v_add_f32_e32 v14, v14, v15
	v_cvt_pk_bf16_f32 v150, v16, v14
	v_lshlrev_b32_e32 v14, 16, v29
	v_and_b32_e32 v15, 0xffff0000, v29
	v_pk_mul_f32 v[16:17], v[32:33], v[14:15]
	v_pk_mul_f32 v[14:15], v[32:33], v[14:15] op_sel:[0,1] op_sel_hi:[1,0]
	v_sub_f32_e32 v16, v16, v17
	v_add_f32_e32 v14, v14, v15
	v_cvt_pk_bf16_f32 v151, v16, v14
	v_lshlrev_b32_e32 v14, 16, v38
	v_and_b32_e32 v15, 0xffff0000, v38
	v_pk_mul_f32 v[16:17], v[46:47], v[14:15]
	v_pk_mul_f32 v[14:15], v[46:47], v[14:15] op_sel:[0,1] op_sel_hi:[1,0]
	v_sub_f32_e32 v16, v16, v17
	v_add_f32_e32 v14, v14, v15
	v_cvt_pk_bf16_f32 v152, v16, v14
	v_lshlrev_b32_e32 v14, 16, v39
	v_and_b32_e32 v15, 0xffff0000, v39
	v_pk_mul_f32 v[16:17], v[48:49], v[14:15]
	v_pk_mul_f32 v[14:15], v[48:49], v[14:15] op_sel:[0,1] op_sel_hi:[1,0]
	v_sub_f32_e32 v16, v16, v17
	v_add_f32_e32 v14, v14, v15
	v_cvt_pk_bf16_f32 v153, v16, v14
	v_lshlrev_b32_e32 v14, 16, v40
	v_and_b32_e32 v15, 0xffff0000, v40
	v_pk_mul_f32 v[16:17], v[42:43], v[14:15]
	v_pk_mul_f32 v[14:15], v[42:43], v[14:15] op_sel:[0,1] op_sel_hi:[1,0]
	v_sub_f32_e32 v16, v16, v17
	v_add_f32_e32 v14, v14, v15
	v_cvt_pk_bf16_f32 v154, v16, v14
	v_lshlrev_b32_e32 v14, 16, v41
	v_and_b32_e32 v15, 0xffff0000, v41
	v_pk_mul_f32 v[16:17], v[44:45], v[14:15]
	v_pk_mul_f32 v[14:15], v[44:45], v[14:15] op_sel:[0,1] op_sel_hi:[1,0]
	v_sub_f32_e32 v16, v16, v17
	v_add_f32_e32 v14, v14, v15
	v_cvt_pk_bf16_f32 v155, v16, v14
	v_lshlrev_b32_e32 v14, 16, v50
	v_and_b32_e32 v15, 0xffff0000, v50
	s_waitcnt vmcnt(0)
	v_pk_mul_f32 v[16:17], v[58:59], v[14:15]
	v_pk_mul_f32 v[14:15], v[58:59], v[14:15] op_sel:[0,1] op_sel_hi:[1,0]
	v_sub_f32_e32 v16, v16, v17
	v_add_f32_e32 v14, v14, v15
	v_cvt_pk_bf16_f32 v156, v16, v14
	v_lshlrev_b32_e32 v14, 16, v51
	v_and_b32_e32 v15, 0xffff0000, v51
	v_pk_mul_f32 v[16:17], v[60:61], v[14:15]
	v_pk_mul_f32 v[14:15], v[60:61], v[14:15] op_sel:[0,1] op_sel_hi:[1,0]
	v_sub_f32_e32 v16, v16, v17
	v_add_f32_e32 v14, v14, v15
	v_cvt_pk_bf16_f32 v157, v16, v14
	v_lshlrev_b32_e32 v14, 16, v52
	v_and_b32_e32 v15, 0xffff0000, v52
	v_pk_mul_f32 v[16:17], v[54:55], v[14:15]
	v_pk_mul_f32 v[14:15], v[54:55], v[14:15] op_sel:[0,1] op_sel_hi:[1,0]
	v_sub_f32_e32 v16, v16, v17
	v_add_f32_e32 v14, v14, v15
	v_cvt_pk_bf16_f32 v158, v16, v14
	v_lshlrev_b32_e32 v14, 16, v53
	v_and_b32_e32 v15, 0xffff0000, v53
	v_pk_mul_f32 v[16:17], v[56:57], v[14:15]
	v_pk_mul_f32 v[14:15], v[56:57], v[14:15] op_sel:[0,1] op_sel_hi:[1,0]
	v_sub_f32_e32 v16, v16, v17
	v_add_f32_e32 v14, v14, v15
	v_cvt_pk_bf16_f32 v159, v16, v14
	v_mov_b32_e32 v14, 0x4000
	v_and_or_b32 v187, v9, 8, v14
	v_bitop3_b32 v9, v13, v12, v62 bitop3:0x36
	v_lshlrev_b32_e32 v188, 4, v9
	v_bitop3_b32 v9, v12, v69, 2 bitop3:0x36
	v_lshlrev_b32_e32 v189, 4, v9
	v_bitop3_b32 v9, v12, v69, 4 bitop3:0x36
	v_lshlrev_b32_e32 v190, 4, v9
	v_bitop3_b32 v9, v12, v69, 6 bitop3:0x36
	v_lshlrev_b32_e32 v191, 4, v9
	v_bitop3_b32 v9, v12, v69, 8 bitop3:0x36
	v_lshlrev_b32_e32 v192, 4, v9
	v_bitop3_b32 v9, v12, v69, 10 bitop3:0x36
	v_lshlrev_b32_e32 v193, 4, v9
	v_bitop3_b32 v9, v12, v69, 12 bitop3:0x36
	v_lshlrev_b32_e32 v194, 4, v9
	v_bitop3_b32 v9, v12, v69, 14 bitop3:0x36
	v_lshlrev_b32_e32 v195, 4, v9
	v_bitop3_b32 v9, v63, v12, 7 bitop3:0x6c
	v_lshlrev_b32_e32 v196, 4, v9
	v_bitop3_b32 v9, v12, v11, 2 bitop3:0x36
	v_lshlrev_b32_e32 v197, 4, v9
	v_bitop3_b32 v9, v12, v11, 4 bitop3:0x36
	v_lshlrev_b32_e32 v198, 4, v9
	v_bitop3_b32 v9, v12, v11, 6 bitop3:0x36
	v_lshlrev_b32_e32 v199, 4, v9
	v_and_b32_e32 v9, 12, v8
	v_or_b32_e32 v11, v66, v9
	v_or_b32_e32 v9, v68, v9
	v_lshlrev_b32_e32 v221, 4, v9
	v_bitop3_b32 v9, v8, 4, 12 bitop3:0x6c
	v_lshlrev_b32_e32 v219, 4, v11
	v_bitop3_b32 v11, v64, v9, v12 bitop3:0xde
	v_bitop3_b32 v9, v64, v9, v67 bitop3:0xde
	v_bitop3_b32 v6, v10, 7, v8 bitop3:0x48
	v_lshlrev_b32_e32 v229, 4, v9
	v_bitop3_b32 v9, v8, 8, 12 bitop3:0x6c
	v_lshl_or_b32 v180, v6, 4, v180
	v_or_b32_e32 v6, 4, v0
	v_lshlrev_b32_e32 v228, 4, v11
	v_bitop3_b32 v11, v64, v9, v12 bitop3:0xde
	v_bitop3_b32 v9, v64, v9, v67 bitop3:0xde
	v_mad_u64_u32 v[6:7], s[14:15], v6, s20, 0
	v_lshlrev_b32_e32 v231, 4, v9
	v_bitop3_b32 v9, v8, 12, v8 bitop3:0xc
	s_sext_i32_i8 s14, s12
	v_mov_b32_e32 v8, 0x600000
	v_mad_i64_i32 v[6:7], s[12:13], s14, v8, v[6:7]
	v_lshl_add_u64 v[4:5], v[6:7], 0, v[4:5]
	v_lshl_add_u64 v[182:183], v[4:5], 0, s[0:1]
	v_mad_u64_u32 v[4:5], s[12:13], v0, s20, 0
	v_mad_i64_i32 v[4:5], s[12:13], s14, v8, v[4:5]
	v_or_b32_e32 v65, v176, v62
	s_waitcnt vmcnt(0) lgkmcnt(0)
	s_barrier
; #define WAIT_TILE(all_) do { if (all_) asm volatile("s_waitcnt vmcnt(0) lgkmcnt(0)" ::: "memory"); \
;         else if constexpr (MODE == 0) asm volatile("s_waitcnt vmcnt(5) lgkmcnt(0)" ::: "memory"); else asm volatile("s_waitcnt vmcnt(4) lgkmcnt(0)" ::: "memory"); \
;         __builtin_amdgcn_s_barrier(); asm volatile("" ::: "memory"); } while (0)
; template <int MODE>
; __device__ __forceinline__ void attn_unit(LAS char* lds, const AttnPtrs& A, int b, int qb) {
;     ...
;     f32x16 o1[4];
; #pragma unroll
;     for (int c = 0; c < 4; ++c) o1[c] = f32x16{};
;     float m1 = -1e30f, l1 = 0.f;
;     unsigned long long mw_next = 0ull;
;     if constexpr (MODE == 1) { mw_next = A.MASK[qrow * 64]; asm volatile("" : "+v"(mw_next)); }
;     bf16x8 pk[4]; float a1 = 1.f;
;     ...
;     WAIT_TILE(true);
;     int st_cur = 0, st_nn = 2;
	v_lshlrev_b32_e32 v230, 4, v11
	v_bitop3_b32 v11, v64, v9, v12 bitop3:0xde
	v_bitop3_b32 v9, v64, v9, v67 bitop3:0xde
	v_lshl_add_u64 v[2:3], v[4:5], 0, v[2:3]
	v_mov_b32_e32 v14, v1
	v_mov_b32_e32 v15, v1
	v_lshlrev_b32_e32 v218, 8, v65
	v_lshlrev_b32_e32 v232, 4, v11
	v_lshlrev_b32_e32 v233, 4, v9
	v_lshl_add_u64 v[184:185], v[2:3], 0, s[0:1]
	v_mov_b32_e32 v0, v1
	v_mov_b32_e32 v2, v1
	v_mov_b32_e32 v3, v1
	v_mov_b32_e32 v4, v1
	v_mov_b32_e32 v5, v1
	v_mov_b32_e32 v6, v1
	v_mov_b32_e32 v7, v1
	v_mov_b32_e32 v8, v1
	v_mov_b32_e32 v9, v1
	v_mov_b32_e32 v10, v1
	v_mov_b32_e32 v11, v1
	v_mov_b32_e32 v12, v1
	v_mov_b32_e32 v13, v1
	v_mov_b64_e32 v[30:31], v[14:15]
	v_mov_b64_e32 v[46:47], v[14:15]
	v_mov_b64_e32 v[62:63], v[14:15]
	v_mov_b64_e32 v[78:79], v[14:15]
	v_mov_b32_e32 v179, s53
	v_or_b32_e32 v220, 0x800, v218
	v_or_b32_e32 v222, 0x1000, v218
	v_or_b32_e32 v223, 0x1800, v218
	v_or_b32_e32 v224, 0x2000, v218
	v_or_b32_e32 v225, 0x2800, v218
	v_or_b32_e32 v226, 0x3000, v218
	v_or_b32_e32 v227, 0x3800, v218
	v_mov_b32_e32 v235, 0xf149f2ca
	v_mov_b32_e32 v253, s97
	v_mov_b32_e32 v252, 0
	v_mov_b64_e32 v[236:237], 0
	v_mov_b64_e32 v[238:239], 0
	v_mov_b64_e32 v[240:241], 0
	v_mov_b64_e32 v[242:243], 0
	v_mov_b64_e32 v[244:245], 0
	v_mov_b64_e32 v[246:247], 0
	v_mov_b64_e32 v[248:249], 0
	v_mov_b64_e32 v[250:251], 0
	v_mov_b32_e32 v234, 0
	v_mov_b64_e32 v[28:29], v[12:13]
	v_mov_b64_e32 v[26:27], v[10:11]
	v_mov_b64_e32 v[24:25], v[8:9]
	v_mov_b64_e32 v[22:23], v[6:7]
	v_mov_b64_e32 v[20:21], v[4:5]
	v_mov_b64_e32 v[18:19], v[2:3]
	v_mov_b64_e32 v[16:17], v[0:1]
	v_mov_b64_e32 v[44:45], v[12:13]
	v_mov_b64_e32 v[42:43], v[10:11]
	v_mov_b64_e32 v[40:41], v[8:9]
	v_mov_b64_e32 v[38:39], v[6:7]
	v_mov_b64_e32 v[36:37], v[4:5]
	v_mov_b64_e32 v[34:35], v[2:3]
	v_mov_b64_e32 v[32:33], v[0:1]
	v_mov_b64_e32 v[60:61], v[12:13]
	v_mov_b64_e32 v[58:59], v[10:11]
	v_mov_b64_e32 v[56:57], v[8:9]
	v_mov_b64_e32 v[54:55], v[6:7]
	v_mov_b64_e32 v[52:53], v[4:5]
	v_mov_b64_e32 v[50:51], v[2:3]
	v_mov_b64_e32 v[48:49], v[0:1]
	v_mov_b64_e32 v[76:77], v[12:13]
	v_mov_b64_e32 v[74:75], v[10:11]
	v_mov_b64_e32 v[72:73], v[8:9]
	v_mov_b64_e32 v[70:71], v[6:7]
	v_mov_b64_e32 v[68:69], v[4:5]
	v_mov_b64_e32 v[66:67], v[2:3]
	v_mov_b64_e32 v[64:65], v[0:1]
	s_mov_b32 s14, 0

; __device__ __forceinline__ float max_x32(float v) { const unsigned u = __float_as_uint(v); auto r = __builtin_amdgcn_permlane32_swap(u, u, false, false); return fmaxf(__uint_as_float(r[0]), __uint_as_float(r[1])); }
; template <bool MASKED>
; __device__ __forceinline__ void softmax_tile(f32x16& s0, f32x16& s1, float& m, float& l, float& alpha, unsigned mlo, unsigned mhi, bf16x8 (&pk)[4]) {
;     ...
;     float mx = fmaxf(s0[0], s1[0]);
; #pragma unroll
;     for (int r = 1; r < 16; ++r) mx = fmaxf(mx, fmaxf(s0[r], s1[r]));
;     mx = max_x32(mx);
;     const float mn = fmaxf(m, mx);
;     alpha = __builtin_amdgcn_exp2f(m - mn); m = mn;
.LBB0_1190:
	s_cmp_gt_i32 s14, s49
	s_cbranch_scc1 .LBB0_1194
	s_mul_i32 s15, s50, 0xa000
	s_add_i32 s15, s15, 0
	v_add_u32_e32 v0, s15, v186
	v_add_u32_e32 v6, v0, v188
	v_add_u32_e32 v14, v0, v189
	ds_read_b128 v[2:5], v6
	ds_read_b128 v[6:9], v6 offset:8192
	ds_read_b128 v[10:13], v14
	ds_read_b128 v[160:163], v14 offset:8192
	v_add_u32_e32 v14, v0, v190
	ds_read_b128 v[164:167], v14
	ds_read_b128 v[168:171], v14 offset:8192
	v_add_u32_e32 v14, v0, v191
	ds_read_b128 v[172:175], v14 offset:8192
	ds_read_b128 v[206:209], v14
	v_add_u32_e32 v14, s15, v177
	s_waitcnt lgkmcnt(0)
	v_mfma_f32_32x32x16_bf16 v[96:111], v[2:5], v[112:115], v[236:251]
	v_mfma_f32_32x32x16_bf16 v[80:95], v[6:9], v[112:115], v[236:251]
	v_mfma_f32_32x32x16_bf16 v[96:111], v[10:13], v[116:119], v[96:111]
	v_mfma_f32_32x32x16_bf16 v[80:95], v[160:163], v[116:119], v[80:95]
	v_mfma_f32_32x32x16_bf16 v[96:111], v[164:167], v[120:123], v[96:111]
	v_mfma_f32_32x32x16_bf16 v[80:95], v[168:171], v[120:123], v[80:95]
	v_mfma_f32_32x32x16_bf16 v[96:111], v[206:209], v[124:127], v[96:111]
	v_mfma_f32_32x32x16_bf16 v[80:95], v[172:175], v[124:127], v[80:95]
	v_add_u32_e32 v6, v0, v192
	v_add_u32_e32 v15, v0, v193
	ds_read_b128 v[2:5], v6
	ds_read_b128 v[6:9], v6 offset:8192
	ds_read_b128 v[10:13], v15
	ds_read_b128 v[160:163], v15 offset:8192
	v_add_u32_e32 v15, v0, v194
	v_add_u32_e32 v0, v0, v195
	ds_read_b128 v[164:167], v15
	ds_read_b128 v[168:171], v15 offset:8192
	ds_read_b128 v[172:175], v0 offset:8192
	ds_read_b128 v[206:209], v0
	s_waitcnt lgkmcnt(0)
	v_mfma_f32_32x32x16_bf16 v[96:111], v[2:5], v[128:131], v[96:111]
	v_mfma_f32_32x32x16_bf16 v[80:95], v[6:9], v[128:131], v[80:95]
	v_mfma_f32_32x32x16_bf16 v[96:111], v[10:13], v[132:135], v[96:111]
	v_mfma_f32_32x32x16_bf16 v[80:95], v[160:163], v[132:135], v[80:95]
	v_mfma_f32_32x32x16_bf16 v[96:111], v[164:167], v[136:139], v[96:111]
	v_mfma_f32_32x32x16_bf16 v[80:95], v[168:171], v[136:139], v[80:95]
	v_mfma_f32_32x32x16_bf16 v[96:111], v[206:209], v[140:143], v[96:111]
	v_mfma_f32_32x32x16_bf16 v[80:95], v[172:175], v[140:143], v[80:95]
	v_add_u32_e32 v0, v14, v196
	ds_read_b128 v[2:5], v0 offset:32768
	ds_read_b128 v[6:9], v0 offset:36864
	v_add_u32_e32 v0, v14, v197
	ds_read_b128 v[10:13], v0 offset:32768
	ds_read_b128 v[160:163], v0 offset:36864
	v_add_u32_e32 v0, v14, v198
	ds_read_b128 v[164:167], v0 offset:32768
	ds_read_b128 v[168:171], v0 offset:36864
	v_add_u32_e32 v0, v14, v199
	ds_read_b128 v[172:175], v0 offset:36864
	ds_read_b128 v[206:209], v0 offset:32768
	s_waitcnt lgkmcnt(0)
	v_mfma_f32_32x32x16_bf16 v[96:111], v[2:5], v[144:147], v[96:111]
	v_mfma_f32_32x32x16_bf16 v[80:95], v[6:9], v[144:147], v[80:95]
	v_mfma_f32_32x32x16_bf16 v[96:111], v[10:13], v[148:151], v[96:111]
	v_mfma_f32_32x32x16_bf16 v[80:95], v[160:163], v[148:151], v[80:95]
	v_mfma_f32_32x32x16_bf16 v[96:111], v[164:167], v[152:155], v[96:111]
	v_mfma_f32_32x32x16_bf16 v[80:95], v[168:171], v[152:155], v[80:95]
	v_mfma_f32_32x32x16_bf16 v[96:111], v[206:209], v[156:159], v[96:111]
	v_mfma_f32_32x32x16_bf16 v[80:95], v[172:175], v[156:159], v[80:95]
	s_nop 11
	v_max3_f32 v160, v96, v97, v98
	v_max3_f32 v161, v99, v100, v101
	v_max3_f32 v162, v102, v103, v104
	v_max3_f32 v163, v105, v106, v107
	v_max3_f32 v164, v108, v109, v110
	v_max3_f32 v165, v111, v80, v81
	v_max3_f32 v166, v82, v83, v84
	v_max3_f32 v167, v85, v86, v87
	v_max3_f32 v168, v88, v89, v90
	v_max3_f32 v169, v91, v92, v93
	v_max3_f32 v160, v160, v161, v162
	v_max3_f32 v163, v163, v164, v165
	v_max3_f32 v166, v166, v167, v168
	v_max3_f32 v169, v169, v94, v95
	v_max3_f32 v160, v160, v163, v166
	v_max_f32_e32 v160, v160, v169
	v_mov_b32_e32 v161, v160
	s_nop 1
	v_permlane32_swap_b32_e32 v160, v161
	v_max_f32_e32 v160, v160, v161
	v_mov_b32_e32 v0, 1.0
	v_mov_b32_e32 v14, v235
	v_cmp_lt_f32_e32 vcc, v253, v160
	s_cbranch_vccz .Lm0_cfast
	v_add_f32_e32 v161, v160, v252
	v_cndmask_b32_e32 v14, v235, v161, vcc
	v_sub_f32_e32 v161, v14, v252
	v_cndmask_b32_e32 v161, 0, v161, vcc
	v_mov_b32_e32 v160, 0x41000000
	v_cndmask_b32_e32 v253, v253, v160, vcc
	v_cndmask_b32_e32 v252, v252, v14, vcc
	v_sub_f32_e32 v0, v235, v14
	v_exp_f32_e32 v0, v0
	v_sub_f32_e32 v96, v96, v161
	v_sub_f32_e32 v97, v97, v161
	v_sub_f32_e32 v98, v98, v161
	v_sub_f32_e32 v99, v99, v161
	v_sub_f32_e32 v100, v100, v161
	v_sub_f32_e32 v101, v101, v161
	v_sub_f32_e32 v102, v102, v161
	v_sub_f32_e32 v103, v103, v161
	v_sub_f32_e32 v104, v104, v161
	v_sub_f32_e32 v105, v105, v161
	v_sub_f32_e32 v106, v106, v161
	v_sub_f32_e32 v107, v107, v161
	v_sub_f32_e32 v108, v108, v161
	v_sub_f32_e32 v109, v109, v161
	v_sub_f32_e32 v110, v110, v161
	v_sub_f32_e32 v111, v111, v161
	v_sub_f32_e32 v80, v80, v161
	v_sub_f32_e32 v81, v81, v161
	v_sub_f32_e32 v82, v82, v161
	v_sub_f32_e32 v83, v83, v161
	v_sub_f32_e32 v84, v84, v161
	v_sub_f32_e32 v85, v85, v161
	v_sub_f32_e32 v86, v86, v161
	v_sub_f32_e32 v87, v87, v161
	v_sub_f32_e32 v88, v88, v161
	v_sub_f32_e32 v89, v89, v161
	v_sub_f32_e32 v90, v90, v161
	v_sub_f32_e32 v91, v91, v161
	v_sub_f32_e32 v92, v92, v161
	v_sub_f32_e32 v93, v93, v161
	v_sub_f32_e32 v94, v94, v161
	v_sub_f32_e32 v95, v95, v161
	v_sub_f32_e32 v236, 0, v252
	v_sub_f32_e32 v237, 0, v252
	v_sub_f32_e32 v238, 0, v252
	v_sub_f32_e32 v239, 0, v252
	v_sub_f32_e32 v240, 0, v252
	v_sub_f32_e32 v241, 0, v252
	v_sub_f32_e32 v242, 0, v252
	v_sub_f32_e32 v243, 0, v252
	v_sub_f32_e32 v244, 0, v252
	v_sub_f32_e32 v245, 0, v252
	v_sub_f32_e32 v246, 0, v252
	v_sub_f32_e32 v247, 0, v252
	v_sub_f32_e32 v248, 0, v252
	v_sub_f32_e32 v249, 0, v252
	v_sub_f32_e32 v250, 0, v252
	v_sub_f32_e32 v251, 0, v252
